# v008
# speedup vs baseline: 1.0004x; 1.0004x over previous
; #define AT_GLOAD(R, V, kt) do { \
;     const char* _kb = (const char*)Kp + (size_t)(kt) * 64 * DK * 2; const char* _vb = (const char*)Vt + (size_t)(kt) * 128; \
;     R##0 = *(const uint4*)(_kb + ko0); \
;     R##1 = *(const uint4*)(_kb + ko1); \
;     if (NKC > 2) R##2 = *(const uint4*)(_kb + ko2); \
;     V##0 = *(const uint4*)(_vb + vo0); \
;     V##1 = *(const uint4*)(_vb + vo1); } while (0)
; template <int DK>
; __device__ __forceinline__ void attn_item(const u16* __restrict__ Qp, const u16* __restrict__ Kp, const u16* __restrict__ Vt,
;                                           u16* __restrict__ Yo, float sc, char* smem) {
;     ...
;   for (int kt = 0; kt < 32; ++kt) {
;     if (PF2) {
;       if (kt + 2 < 32) { if (kt & 1) AT_GLOAD(kr, vr, kt + 2); else AT_GLOAD(ks, vs, kt + 2); }
;     } else {
;       if (kt + 1 < 32) AT_GLOAD(kr, vr, kt + 1);
;     }
;     const char* kb = smem + (kt & 1) * STB;
;     const char* vb = kb + KTB;
;     f32x4 S[4][2];
; #pragma unroll
;     for (int mt = 0; mt < 4; ++mt) { S[mt][0] = f32x4{0, 0, 0, 0}; S[mt][1] = f32x4{0, 0, 0, 0}; }
; #pragma unroll
;     for (int ks = 0; ks < NKS; ++ks)
; #pragma unroll
;       for (int mt = 0; mt < 4; ++mt) {
;         bf16x8 a = *(const bf16x8*)(kb + (mt * 16 + fr) * KSTR + (ks * 32 + g * 8) * 2);
;         S[mt][0] = __builtin_amdgcn_mfma_f32_16x16x32_bf16(a, qf[0][ks], S[mt][0], 0, 0, 0);
;         S[mt][1] = __builtin_amdgcn_mfma_f32_16x16x32_bf16(a, qf[1][ks], S[mt][1], 0, 0, 0);
;       }
;     bf16x8 pf[2][2];
; #pragma unroll
;     for (int n = 0; n < 2; ++n) {
;       float mx = S[0][n][0];
; #pragma unroll
;       for (int mt = 0; mt < 4; ++mt)
; #pragma unroll
;         for (int j = 0; j < 4; ++j) mx = fmaxf(mx, S[mt][n][j]);
;       mx = fmaxf(mx, shx(mx, 16, lane));
;       mx = fmaxf(mx, shx(mx, 32, lane));
;       float mnew = fmaxf(mrun[n], mx * sc);
;       float alpha = __builtin_amdgcn_exp2f(mrun[n] - mnew);
;       mrun[n] = mnew;
;       float ls = 0.f;
; #pragma unroll
;       for (int mt = 0; mt < 4; ++mt)
; #pragma unroll
;         for (int j = 0; j < 4; ++j) { float pv = __builtin_amdgcn_exp2f(S[mt][n][j] * sc - mnew); S[mt][n][j] = pv; ls += pv; }
.LBB0_2466:
	s_add_i32 s2, s3, 1
	s_bitcmp1_b32 s3, 0
	s_cselect_b32 s3, 0x8c00, 0
	v_or_b32_e32 v112, s3, v178
	v_add_u32_e32 v168, v112, v196
	ds_read_b128 v[208:211], v168 offset:0
	ds_read_b128 v[212:215], v168 offset:4352
	ds_read_b128 v[216:219], v168 offset:8704
	ds_read_b128 v[240:243], v168 offset:13056
	ds_read_b128 v[244:247], v168 offset:64
	ds_read_b128 v[248:251], v168 offset:4416
	v_mov_b32_e32 v155, v203
	v_mov_b32_e32 v154, v204
	s_waitcnt lgkmcnt(5)
	v_mfma_f32_16x16x32_bf16 v[116:119], v[208:211], v[24:27], 0
	v_lshl_add_u64 v[48:49], v[150:151], 0, s[10:11]
	global_load_dwordx4 v[48:51], v[48:49], off
	v_mfma_f32_16x16x32_bf16 v[132:135], v[208:211], v[28:31], 0
	ds_read_b128 v[208:211], v168 offset:8768
	s_waitcnt lgkmcnt(5)
	v_mfma_f32_16x16x32_bf16 v[124:127], v[212:215], v[24:27], 0
	v_lshl_add_u64 v[52:53], v[152:153], 0, s[10:11]
	global_load_dwordx4 v[52:55], v[52:53], off
	v_mfma_f32_16x16x32_bf16 v[128:131], v[212:215], v[28:31], 0
	ds_read_b128 v[212:215], v168 offset:13120
	s_waitcnt lgkmcnt(5)
	v_mfma_f32_16x16x32_bf16 v[120:123], v[216:219], v[24:27], 0
	v_lshl_add_u64 v[56:57], v[146:147], 0, s[10:11]
	global_load_dwordx4 v[56:59], v[56:57], off
	v_mfma_f32_16x16x32_bf16 v[136:139], v[216:219], v[28:31], 0
	ds_read_b128 v[216:219], v168 offset:128
	s_waitcnt lgkmcnt(5)
	v_mfma_f32_16x16x32_bf16 v[186:189], v[240:243], v[24:27], 0
	v_lshl_add_u64 v[60:61], v[148:149], 0, s[10:11]
	global_load_dwordx4 v[60:63], v[60:61], off
	v_mfma_f32_16x16x32_bf16 v[140:143], v[240:243], v[28:31], 0
	ds_read_b128 v[240:243], v168 offset:4480
	s_waitcnt lgkmcnt(5)
	v_mfma_f32_16x16x32_bf16 v[116:119], v[244:247], v[16:19], v[116:119]
	s_bitcmp1_b32 s2, 0
	v_lshl_add_u64 v[146:147], v[146:147], 0, s[60:61]
	v_mfma_f32_16x16x32_bf16 v[132:135], v[244:247], v[20:23], v[132:135]
	ds_read_b128 v[244:247], v168 offset:8832
	s_waitcnt lgkmcnt(5)
	v_mfma_f32_16x16x32_bf16 v[124:127], v[248:251], v[16:19], v[124:127]
	v_lshl_add_u64 v[148:149], v[148:149], 0, s[60:61]
	v_mfma_f32_16x16x32_bf16 v[128:131], v[248:251], v[20:23], v[128:131]
	ds_read_b128 v[248:251], v168 offset:13184
	s_waitcnt lgkmcnt(5)
	v_mfma_f32_16x16x32_bf16 v[120:123], v[208:211], v[16:19], v[120:123]
	v_lshl_add_u64 v[150:151], v[150:151], 0, s[16:17]
	v_mfma_f32_16x16x32_bf16 v[136:139], v[208:211], v[20:23], v[136:139]
	ds_read_b128 v[208:211], v168 offset:192
	s_waitcnt lgkmcnt(5)
	v_mfma_f32_16x16x32_bf16 v[186:189], v[212:215], v[16:19], v[186:189]
	v_lshl_add_u64 v[152:153], v[152:153], 0, s[16:17]
	v_mfma_f32_16x16x32_bf16 v[140:143], v[212:215], v[20:23], v[140:143]
	ds_read_b128 v[212:215], v168 offset:4544
	s_waitcnt lgkmcnt(5)
	v_mfma_f32_16x16x32_bf16 v[116:119], v[216:219], v[8:11], v[116:119]
	v_mfma_f32_16x16x32_bf16 v[132:135], v[216:219], v[12:15], v[132:135]
	ds_read_b128 v[216:219], v168 offset:8896
	s_waitcnt lgkmcnt(5)
	v_mfma_f32_16x16x32_bf16 v[124:127], v[240:243], v[8:11], v[124:127]
	v_mfma_f32_16x16x32_bf16 v[128:131], v[240:243], v[12:15], v[128:131]
	ds_read_b128 v[240:243], v168 offset:13248
	s_waitcnt lgkmcnt(5)
	v_mfma_f32_16x16x32_bf16 v[120:123], v[244:247], v[8:11], v[120:123]
	v_mfma_f32_16x16x32_bf16 v[136:139], v[244:247], v[12:15], v[136:139]
	s_waitcnt lgkmcnt(4)
	v_mfma_f32_16x16x32_bf16 v[186:189], v[248:251], v[8:11], v[186:189]
	v_mfma_f32_16x16x32_bf16 v[140:143], v[248:251], v[12:15], v[140:143]
	s_waitcnt lgkmcnt(3)
	v_mfma_f32_16x16x32_bf16 v[116:119], v[208:211], v[0:3], v[116:119]
	v_mfma_f32_16x16x32_bf16 v[132:135], v[208:211], v[4:7], v[132:135]
	s_waitcnt lgkmcnt(2)
	v_mfma_f32_16x16x32_bf16 v[124:127], v[212:215], v[0:3], v[124:127]
	v_mfma_f32_16x16x32_bf16 v[128:131], v[212:215], v[4:7], v[128:131]
	s_waitcnt lgkmcnt(1)
	v_mfma_f32_16x16x32_bf16 v[120:123], v[216:219], v[0:3], v[120:123]
	v_mfma_f32_16x16x32_bf16 v[136:139], v[216:219], v[4:7], v[136:139]
	s_waitcnt lgkmcnt(0)
	v_mfma_f32_16x16x32_bf16 v[186:189], v[240:243], v[0:3], v[186:189]
	v_mfma_f32_16x16x32_bf16 v[140:143], v[240:243], v[4:7], v[140:143]
	v_max_f32_e32 v112, v117, v117
	v_max_f32_e32 v113, v116, v116
	v_max_f32_e32 v112, v113, v112
	v_max3_f32 v112, v112, v118, v119
	v_max3_f32 v112, v112, v124, v125
	v_max3_f32 v112, v112, v126, v127
	v_max3_f32 v112, v112, v120, v121
	v_max3_f32 v112, v112, v122, v123
	v_max3_f32 v112, v112, v186, v187
	v_max3_f32 v112, v112, v188, v189
	ds_bpermute_b32 v113, v191, v112
	s_waitcnt lgkmcnt(0)
	v_max_f32_e32 v113, v113, v113
	v_max_f32_e32 v112, v112, v113
	ds_bpermute_b32 v113, v192, v112
	s_waitcnt lgkmcnt(0)
	v_max_f32_e32 v113, v113, v113
	v_max_f32_e32 v112, v112, v113
	v_mul_f32_e32 v112, 0x3e0293ee, v112
	v_max_f32_e32 v113, v155, v155
	v_max_f32_e32 v203, v113, v112
	v_fma_f32 v113, v116, s0, -v203
	v_sub_f32_e32 v112, v155, v203
	v_exp_f32_e32 v155, v113
	v_fma_f32 v113, v117, s0, -v203
	v_exp_f32_e32 v157, v113
	v_fma_f32 v113, v118, s0, -v203
	v_exp_f32_e32 v159, v113
	v_fma_f32 v113, v119, s0, -v203
	v_exp_f32_e32 v161, v113
	v_fma_f32 v113, v124, s0, -v203
	v_exp_f32_e32 v163, v113
	v_fma_f32 v113, v125, s0, -v203
	v_exp_f32_e32 v190, v112
	v_exp_f32_e32 v165, v113
	v_fma_f32 v113, v126, s0, -v203
	v_exp_f32_e32 v167, v113
	v_fma_f32 v113, v127, s0, -v203
	v_exp_f32_e32 v169, v113
	v_fma_f32 v113, v120, s0, -v203
	v_exp_f32_e32 v171, v113
	v_fma_f32 v113, v121, s0, -v203
	v_pk_mul_f32 v[120:121], v[88:89], v[190:191] op_sel_hi:[1,0]
	v_pk_mul_f32 v[88:89], v[100:101], v[190:191] op_sel_hi:[1,0]
	v_max_f32_e32 v100, v133, v133
	v_max_f32_e32 v101, v132, v132
	v_max_f32_e32 v100, v101, v100
	v_max3_f32 v100, v100, v134, v135
	v_max3_f32 v100, v100, v128, v129
	v_max3_f32 v100, v100, v130, v131
	v_max3_f32 v100, v100, v136, v137
	v_max3_f32 v100, v100, v138, v139
	v_max3_f32 v100, v100, v140, v141
	v_max3_f32 v100, v100, v142, v143
	ds_bpermute_b32 v101, v191, v100
	v_exp_f32_e32 v173, v113
	v_fma_f32 v113, v122, s0, -v203
	v_exp_f32_e32 v175, v113
	v_fma_f32 v113, v123, s0, -v203
	s_waitcnt lgkmcnt(0)
; template <int DK>
; __device__ __forceinline__ void attn_item(const u16* __restrict__ Qp, const u16* __restrict__ Kp, const u16* __restrict__ Vt,
;                                           u16* __restrict__ Yo, float sc, char* smem) {
;     ...
;       float mnew = fmaxf(mrun[n], mx * sc);
;       float alpha = __builtin_amdgcn_exp2f(mrun[n] - mnew);
;       mrun[n] = mnew;
;       float ls = 0.f;
; #pragma unroll
;       for (int mt = 0; mt < 4; ++mt)
; #pragma unroll
;         for (int j = 0; j < 4; ++j) { float pv = __builtin_amdgcn_exp2f(S[mt][n][j] * sc - mnew); S[mt][n][j] = pv; ls += pv; }
;       lrun[n] = lrun[n] * alpha + ls;
; #pragma unroll
;       for (int i = 0; i < 8; ++i) O[i][n] *= alpha;
; #pragma unroll
;       for (int k2 = 0; k2 < 2; ++k2) {
;         u32x4 pk;
;         pk[0] = pack2(S[2 * k2][n][0], S[2 * k2][n][1]);
;         pk[1] = pack2(S[2 * k2][n][2], S[2 * k2][n][3]);
;         pk[2] = pack2(S[2 * k2 + 1][n][0], S[2 * k2 + 1][n][1]);
;         pk[3] = pack2(S[2 * k2 + 1][n][2], S[2 * k2 + 1][n][3]);
;         pf[n][k2] = __builtin_bit_cast(bf16x8, pk);
;       }
;     }
; #pragma unroll
;     for (int k2 = 0; k2 < 2; ++k2)
; #pragma unroll
;       for (int mv = 0; mv < 8; ++mv) {
;         const char* ap = vb + (mv * 16 + fr) * VSTR + (k2 * 32 + 4 * g) * 2;
;         uint2 h0 = *(const uint2*)(ap);
;         uint2 h1 = *(const uint2*)(ap + 32);
;         u32x4 avu = {h0.x, h0.y, h1.x, h1.y};
;         bf16x8 av = __builtin_bit_cast(bf16x8, avu);
;         O[mv][0] = __builtin_amdgcn_mfma_f32_16x16x32_bf16(av, pf[0][k2], O[mv][0], 0, 0, 0);
;         O[mv][1] = __builtin_amdgcn_mfma_f32_16x16x32_bf16(av, pf[1][k2], O[mv][1], 0, 0, 0);
	v_max_f32_e32 v101, v101, v101
	v_max_f32_e32 v100, v100, v101
	ds_bpermute_b32 v101, v192, v100
	v_pk_mul_f32 v[122:123], v[90:91], v[190:191] op_sel_hi:[1,0]
	v_pk_mul_f32 v[90:91], v[102:103], v[190:191] op_sel_hi:[1,0]
	v_exp_f32_e32 v181, v113
	v_fma_f32 v113, v186, s0, -v203
	s_waitcnt lgkmcnt(0)
	v_max_f32_e32 v101, v101, v101
	v_max_f32_e32 v100, v100, v101
	v_mul_f32_e32 v100, 0x3e0293ee, v100
	v_max_f32_e32 v101, v154, v154
	v_max_f32_e32 v204, v101, v100
	v_fma_f32 v100, v132, s0, -v204
	v_sub_f32_e32 v102, v154, v204
	v_exp_f32_e32 v154, v100
	v_fma_f32 v100, v133, s0, -v204
	v_exp_f32_e32 v156, v100
	v_fma_f32 v100, v134, s0, -v204
	v_exp_f32_e32 v158, v100
	v_fma_f32 v100, v135, s0, -v204
	v_exp_f32_e32 v160, v100
	v_fma_f32 v100, v128, s0, -v204
	v_exp_f32_e32 v162, v100
	v_fma_f32 v100, v129, s0, -v204
	v_exp_f32_e32 v164, v100
	v_pk_add_f32 v[100:101], v[154:155], 0 op_sel_hi:[1,0]
	v_fma_f32 v103, v130, s0, -v204
	v_pk_add_f32 v[100:101], v[156:157], v[100:101]
	v_exp_f32_e32 v166, v103
	v_pk_add_f32 v[100:101], v[158:159], v[100:101]
	v_fma_f32 v103, v131, s0, -v204
	v_pk_add_f32 v[100:101], v[160:161], v[100:101]
	v_exp_f32_e32 v168, v103
	v_fma_f32 v103, v136, s0, -v204
	v_pk_add_f32 v[100:101], v[162:163], v[100:101]
	v_exp_f32_e32 v170, v103
	v_fma_f32 v103, v137, s0, -v204
	v_pk_add_f32 v[100:101], v[164:165], v[100:101]
	v_exp_f32_e32 v172, v103
	v_fma_f32 v103, v138, s0, -v204
	v_exp_f32_e32 v174, v103
	v_fma_f32 v103, v139, s0, -v204
	v_pk_add_f32 v[100:101], v[166:167], v[100:101]
	v_exp_f32_e32 v180, v103
	v_fma_f32 v103, v140, s0, -v204
	v_pk_add_f32 v[100:101], v[168:169], v[100:101]
	v_exp_f32_e32 v183, v113
	v_fma_f32 v113, v187, s0, -v203
	v_exp_f32_e32 v182, v103
	v_fma_f32 v103, v141, s0, -v204
	v_pk_add_f32 v[100:101], v[170:171], v[100:101]
	v_exp_f32_e32 v185, v113
	v_fma_f32 v113, v188, s0, -v203
	v_exp_f32_e32 v184, v103
	v_fma_f32 v103, v142, s0, -v204
	v_pk_add_f32 v[100:101], v[172:173], v[100:101]
	v_exp_f32_e32 v187, v113
	v_fma_f32 v113, v189, s0, -v203
	v_exp_f32_e32 v186, v103
	v_fma_f32 v103, v143, s0, -v204
	v_pk_add_f32 v[100:101], v[174:175], v[100:101]
	v_exp_f32_e32 v189, v113
	v_exp_f32_e32 v188, v103
	v_pk_add_f32 v[100:101], v[180:181], v[100:101]
	v_exp_f32_e32 v140, v102
	v_pk_add_f32 v[100:101], v[182:183], v[100:101]
	v_mov_b32_e32 v141, v190
	v_pk_add_f32 v[100:101], v[184:185], v[100:101]
	v_pk_mul_f32 v[136:137], v[32:33], v[140:141] op_sel_hi:[1,0]
	v_pk_add_f32 v[100:101], v[186:187], v[100:101]
	v_pk_mul_f32 v[32:33], v[76:77], v[140:141] op_sel_hi:[1,0]
	v_pk_add_f32 v[100:101], v[188:189], v[100:101]
	v_cvt_pk_bf16_f32 v77, v174, v180
	v_pk_fma_f32 v[144:145], v[144:145], v[140:141], v[100:101]
	v_pk_mul_f32 v[100:101], v[64:65], v[140:141] op_sel_hi:[1,0]
	v_or_b32_e32 v64, s3, v193
	v_add_u32_e32 v174, v64, v194
	v_pk_mul_f32 v[112:113], v[80:81], v[190:191] op_sel_hi:[1,0]
	v_pk_mul_f32 v[80:81], v[96:97], v[190:191] op_sel_hi:[1,0]
	v_cvt_pk_bf16_f32 v97, v175, v181
	v_add_u32_e32 v175, 0x4000, v174
	v_pk_mul_f32 v[102:103], v[66:67], v[140:141] op_sel_hi:[1,0]
	ds_read2_b64 v[64:67], v175 offset0:128 offset1:132
	v_pk_mul_f32 v[126:127], v[94:95], v[190:191] op_sel_hi:[1,0]
	v_pk_mul_f32 v[124:125], v[92:93], v[190:191] op_sel_hi:[1,0]
	v_pk_mul_f32 v[118:119], v[86:87], v[190:191] op_sel_hi:[1,0]
	v_pk_mul_f32 v[116:117], v[84:85], v[190:191] op_sel_hi:[1,0]
	v_cvt_pk_bf16_f32 v84, v155, v157
	v_cvt_pk_bf16_f32 v85, v159, v161
	v_cvt_pk_bf16_f32 v86, v163, v165
	v_cvt_pk_bf16_f32 v87, v167, v169
	v_pk_mul_f32 v[138:139], v[34:35], v[140:141] op_sel_hi:[1,0]
	v_pk_mul_f32 v[134:135], v[38:39], v[140:141] op_sel_hi:[1,0]
	v_pk_mul_f32 v[132:133], v[36:37], v[140:141] op_sel_hi:[1,0]
	v_cvt_pk_bf16_f32 v36, v154, v156
	v_cvt_pk_bf16_f32 v37, v158, v160
	v_cvt_pk_bf16_f32 v38, v162, v164
	v_cvt_pk_bf16_f32 v39, v166, v168
	v_add_u32_e32 v180, 0x4800, v174
	v_pk_mul_f32 v[94:95], v[106:107], v[190:191] op_sel_hi:[1,0]
	v_pk_mul_f32 v[92:93], v[104:105], v[190:191] op_sel_hi:[1,0]
	v_pk_mul_f32 v[130:131], v[42:43], v[140:141] op_sel_hi:[1,0]
	v_pk_mul_f32 v[128:129], v[40:41], v[140:141] op_sel_hi:[1,0]
	v_pk_mul_f32 v[106:107], v[46:47], v[140:141] op_sel_hi:[1,0]
	v_pk_mul_f32 v[104:105], v[44:45], v[140:141] op_sel_hi:[1,0]
	v_pk_mul_f32 v[46:47], v[70:71], v[140:141] op_sel_hi:[1,0]
	v_pk_mul_f32 v[44:45], v[68:69], v[140:141] op_sel_hi:[1,0]
	v_pk_mul_f32 v[42:43], v[74:75], v[140:141] op_sel_hi:[1,0]
	v_pk_mul_f32 v[40:41], v[72:73], v[140:141] op_sel_hi:[1,0]
	v_pk_mul_f32 v[34:35], v[78:79], v[140:141] op_sel_hi:[1,0]
	s_waitcnt lgkmcnt(0)
	v_mfma_f32_16x16x32_bf16 v[140:143], v[64:67], v[84:87], v[124:127]
	v_add_u32_e32 v181, 0x5000, v174
	v_cvt_pk_bf16_f32 v96, v171, v173
	v_cvt_pk_bf16_f32 v76, v170, v172
	v_mfma_f32_16x16x32_bf16 v[136:139], v[64:67], v[36:39], v[136:139]
	ds_read2_b64 v[64:67], v180 offset0:160 offset1:164
	v_pk_mul_f32 v[114:115], v[82:83], v[190:191] op_sel_hi:[1,0]
	v_pk_mul_f32 v[110:111], v[110:111], v[190:191] op_sel_hi:[1,0]
	s_waitcnt lgkmcnt(0)
	v_mfma_f32_16x16x32_bf16 v[154:157], v[64:67], v[84:87], v[120:123]
	v_mul_f32_e64 v108, v108, v190
	v_mul_f32_e64 v109, v109, v190
	v_pk_mul_f32 v[82:83], v[98:99], v[190:191] op_sel_hi:[1,0]
	v_cvt_pk_bf16_f32 v98, v183, v185
	v_mfma_f32_16x16x32_bf16 v[132:135], v[64:67], v[36:39], v[132:135]
	ds_read2_b64 v[64:67], v181 offset0:192 offset1:196
	v_cvt_pk_bf16_f32 v99, v187, v189
	v_cvt_pk_bf16_f32 v78, v182, v184
	s_waitcnt lgkmcnt(0)
; #define AT_LWRITE(R, V, bi) do { char* _base = smem + (bi) * STB; \
;     *(uint4*)(_base + krow0 * KSTR + kcc0 * 16) = R##0; \
;     *(uint4*)(_base + krow1 * KSTR + kcc1 * 16) = R##1; \
;     if (NKC > 2) *(uint4*)(_base + krow2 * KSTR + kcc2 * 16) = R##2; \
;     *(uint4*)(_base + KTB + vrow0 * VSTR + vcc * 16) = V##0; \
;     *(uint4*)(_base + KTB + vrow1 * VSTR + vcc * 16) = V##1; } while (0)
; template <int DK>
; __device__ __forceinline__ void attn_item(const u16* __restrict__ Qp, const u16* __restrict__ Kp, const u16* __restrict__ Vt,
;                                           u16* __restrict__ Yo, float sc, char* smem) {
;     ...
; #pragma unroll
;     for (int ks = 0; ks < NKS; ++ks)
; #pragma unroll
;       for (int mt = 0; mt < 4; ++mt) {
;         bf16x8 a = *(const bf16x8*)(kb + (mt * 16 + fr) * KSTR + (ks * 32 + g * 8) * 2);
;         S[mt][0] = __builtin_amdgcn_mfma_f32_16x16x32_bf16(a, qf[0][ks], S[mt][0], 0, 0, 0);
;         S[mt][1] = __builtin_amdgcn_mfma_f32_16x16x32_bf16(a, qf[1][ks], S[mt][1], 0, 0, 0);
;       }
;     ...
; #pragma unroll
;     for (int k2 = 0; k2 < 2; ++k2)
; #pragma unroll
;       for (int mv = 0; mv < 8; ++mv) {
;         const char* ap = vb + (mv * 16 + fr) * VSTR + (k2 * 32 + 4 * g) * 2;
;         uint2 h0 = *(const uint2*)(ap);
;         uint2 h1 = *(const uint2*)(ap + 32);
;         u32x4 avu = {h0.x, h0.y, h1.x, h1.y};
;         bf16x8 av = __builtin_bit_cast(bf16x8, avu);
;         O[mv][0] = __builtin_amdgcn_mfma_f32_16x16x32_bf16(av, pf[0][k2], O[mv][0], 0, 0, 0);
;         O[mv][1] = __builtin_amdgcn_mfma_f32_16x16x32_bf16(av, pf[1][k2], O[mv][1], 0, 0, 0);
;       }
;     if (kt + 1 < 32) { if (PF2 && (kt & 1)) AT_LWRITE(ks, vs, (kt + 1) & 1); else AT_LWRITE(kr, vr, (kt + 1) & 1); }
;     __syncthreads();
	v_mfma_f32_16x16x32_bf16 v[162:165], v[64:67], v[36:39], v[128:131]
	s_nop 2
	v_add_u32_e32 v130, 0x5800, v174
	v_add_u32_e32 v128, 0x7800, v174
	v_add_u32_e32 v129, 0x8000, v174
	v_mfma_f32_16x16x32_bf16 v[158:161], v[64:67], v[84:87], v[116:119]
	ds_read2_b64 v[64:67], v130 offset0:224 offset1:228
	v_cvt_pk_bf16_f32 v79, v186, v188
	s_cselect_b32 s3, 0x8c00, 0
	s_waitcnt lgkmcnt(0)
	v_mfma_f32_16x16x32_bf16 v[170:173], v[64:67], v[36:39], v[104:107]
	s_nop 2
	v_add_u32_e32 v104, 0x6800, v174
	ds_read2_b64 v[68:71], v104 offset1:4
	v_add_u32_e32 v105, 0x7000, v174
	v_mfma_f32_16x16x32_bf16 v[166:169], v[64:67], v[84:87], v[112:115]
	s_cmp_lg_u32 s2, 31
	s_waitcnt lgkmcnt(0)
	v_mfma_f32_16x16x32_bf16 v[64:67], v[68:71], v[84:87], v[108:111]
	v_mfma_f32_16x16x32_bf16 v[68:71], v[68:71], v[36:39], v[100:103]
	s_nop 2
	ds_read2_b64 v[100:103], v105 offset0:32 offset1:36
	s_waitcnt lgkmcnt(0)
	v_mfma_f32_16x16x32_bf16 v[72:75], v[100:103], v[84:87], v[92:95]
	v_mfma_f32_16x16x32_bf16 v[100:103], v[100:103], v[36:39], v[44:47]
	s_nop 2
	ds_read2_b64 v[44:47], v128 offset0:64 offset1:68
	s_waitcnt lgkmcnt(0)
	v_mfma_f32_16x16x32_bf16 v[124:127], v[44:47], v[36:39], v[40:43]
	s_nop 2
	ds_read2_b64 v[40:43], v129 offset0:96 offset1:100
	s_waitcnt lgkmcnt(0)
	v_mfma_f32_16x16x32_bf16 v[116:119], v[40:43], v[36:39], v[32:35]
	ds_read2_b64 v[36:39], v180 offset0:168 offset1:172
	s_nop 1
	ds_read2_b64 v[32:35], v175 offset0:136 offset1:140
	v_mfma_f32_16x16x32_bf16 v[120:123], v[44:47], v[84:87], v[88:91]
	ds_read2_b64 v[44:47], v130 offset0:232 offset1:236
	s_waitcnt lgkmcnt(2)
	v_mfma_f32_16x16x32_bf16 v[88:91], v[36:39], v[96:99], v[154:157]
	v_mfma_f32_16x16x32_bf16 v[36:39], v[36:39], v[76:79], v[132:135]
	s_nop 2
	ds_read2_b64 v[130:133], v104 offset0:8 offset1:12
	s_waitcnt lgkmcnt(0)
	v_mfma_f32_16x16x32_bf16 v[108:111], v[130:133], v[96:99], v[64:67]
	v_mfma_f32_16x16x32_bf16 v[64:67], v[130:133], v[76:79], v[68:71]
	s_nop 2
	ds_read2_b64 v[68:71], v105 offset0:40 offset1:44
	s_waitcnt lgkmcnt(0)
	v_mfma_f32_16x16x32_bf16 v[104:107], v[68:71], v[96:99], v[72:75]
	s_nop 2
	ds_read2_b64 v[72:75], v128 offset0:72 offset1:76
	v_mfma_f32_16x16x32_bf16 v[112:115], v[40:43], v[84:87], v[80:83]
	ds_read2_b64 v[40:43], v181 offset0:200 offset1:204
	v_mfma_f32_16x16x32_bf16 v[68:71], v[68:71], v[76:79], v[100:103]
	s_waitcnt lgkmcnt(1)
	v_mfma_f32_16x16x32_bf16 v[100:103], v[72:75], v[96:99], v[120:123]
	s_nop 2
	ds_read2_b64 v[120:123], v129 offset0:104 offset1:108
	v_mfma_f32_16x16x32_bf16 v[92:95], v[32:35], v[96:99], v[140:143]
	v_mfma_f32_16x16x32_bf16 v[32:35], v[32:35], v[76:79], v[136:139]
	s_waitcnt lgkmcnt(1)
	v_mfma_f32_16x16x32_bf16 v[84:87], v[40:43], v[96:99], v[158:161]
	v_mfma_f32_16x16x32_bf16 v[40:43], v[40:43], v[76:79], v[162:165]
	v_mfma_f32_16x16x32_bf16 v[80:83], v[44:47], v[96:99], v[166:169]
	v_mfma_f32_16x16x32_bf16 v[44:47], v[44:47], v[76:79], v[170:173]
	v_mfma_f32_16x16x32_bf16 v[72:75], v[72:75], v[76:79], v[124:127]
	s_waitcnt lgkmcnt(0)
	v_mfma_f32_16x16x32_bf16 v[96:99], v[120:123], v[96:99], v[112:115]
	v_mfma_f32_16x16x32_bf16 v[76:79], v[120:123], v[76:79], v[116:119]
	s_nop 1
	v_add3_u32 v112, s3, v198, v195
	v_add3_u32 v113, s3, v197, v195
	v_add3_u32 v114, s3, v201, v202
	v_add3_u32 v115, s3, v199, v200
	s_mov_b32 s3, s2
	s_waitcnt vmcnt(3)
	ds_write_b128 v115, v[48:51]
	s_waitcnt vmcnt(2)
	ds_write_b128 v114, v[52:55]
	s_waitcnt vmcnt(1)
	ds_write_b128 v113, v[56:59] offset:17408
	s_waitcnt vmcnt(0)
	ds_write_b128 v112, v[60:63] offset:17408
	s_waitcnt lgkmcnt(0)
	s_barrier
	s_cbranch_scc1 .LBB0_2466
	v_add_u32_e32 v124, v178, v196
	ds_read_b128 v[48:51], v124 offset:35840
	ds_read_b128 v[56:59], v124 offset:40192
	ds_read_b128 v[112:115], v124 offset:44544
	ds_read_b128 v[120:123], v124 offset:48896
	s_mov_b32 s9, s35
	s_lshl_b64 s[2:3], s[8:9], 21
	s_lshl_b32 s8, s13, 10
	v_readlane_b32 s9, v255, 49
	s_add_u32 s2, s9, s2
	s_waitcnt lgkmcnt(3)
	v_mfma_f32_16x16x32_bf16 v[52:55], v[48:51], v[24:27], 0
	v_readlane_b32 s9, v255, 50
	s_addc_u32 s3, s9, s3
	s_add_u32 s2, s2, s8
	v_mfma_f32_16x16x32_bf16 v[48:51], v[48:51], v[28:31], 0
	s_addc_u32 s3, s3, 0
	s_lshl_b32 s8, s12, 8
	s_add_u32 s8, s2, s8
	s_waitcnt lgkmcnt(2)
	v_mfma_f32_16x16x32_bf16 v[60:63], v[56:59], v[24:27], 0
	s_addc_u32 s9, s3, 0
	s_mov_b64 s[10:11], -1
	v_mov_b32_e32 v223, v205
	v_mfma_f32_16x16x32_bf16 v[56:59], v[56:59], v[28:31], 0
	s_waitcnt lgkmcnt(1)
	v_mfma_f32_16x16x32_bf16 v[116:119], v[112:115], v[24:27], 0
	v_mfma_f32_16x16x32_bf16 v[112:115], v[112:115], v[28:31], 0
	s_waitcnt lgkmcnt(0)
	v_mfma_f32_16x16x32_bf16 v[24:27], v[120:123], v[24:27], 0
	v_mfma_f32_16x16x32_bf16 v[28:31], v[120:123], v[28:31], 0
	ds_read_b128 v[120:123], v124 offset:35904
	s_waitcnt lgkmcnt(0)
	v_mfma_f32_16x16x32_bf16 v[52:55], v[120:123], v[16:19], v[52:55]
	v_mfma_f32_16x16x32_bf16 v[48:51], v[120:123], v[20:23], v[48:51]
	ds_read_b128 v[120:123], v124 offset:40256
	s_waitcnt lgkmcnt(0)
	v_mfma_f32_16x16x32_bf16 v[60:63], v[120:123], v[16:19], v[60:63]
	v_mfma_f32_16x16x32_bf16 v[56:59], v[120:123], v[20:23], v[56:59]
	ds_read_b128 v[120:123], v124 offset:44608
	s_waitcnt lgkmcnt(0)
	v_mfma_f32_16x16x32_bf16 v[116:119], v[120:123], v[16:19], v[116:119]
	v_mfma_f32_16x16x32_bf16 v[112:115], v[120:123], v[20:23], v[112:115]
	ds_read_b128 v[120:123], v124 offset:48960
	s_waitcnt lgkmcnt(0)
	v_mfma_f32_16x16x32_bf16 v[16:19], v[120:123], v[16:19], v[24:27]
	s_nop 2
	ds_read_b128 v[24:27], v124 offset:35968
	v_mfma_f32_16x16x32_bf16 v[20:23], v[120:123], v[20:23], v[28:31]
	s_waitcnt lgkmcnt(0)
; template <int DK>
; __device__ __forceinline__ void attn_item(const u16* __restrict__ Qp, const u16* __restrict__ Kp, const u16* __restrict__ Vt,
;                                           u16* __restrict__ Yo, float sc, char* smem) {
;     ...
;     for (int ks = 0; ks < NKS; ++ks)
; #pragma unroll
;       for (int mt = 0; mt < 4; ++mt) {
;         bf16x8 a = *(const bf16x8*)(kb + (mt * 16 + fr) * KSTR + (ks * 32 + g * 8) * 2);
;         S[mt][0] = __builtin_amdgcn_mfma_f32_16x16x32_bf16(a, qf[0][ks], S[mt][0], 0, 0, 0);
;         S[mt][1] = __builtin_amdgcn_mfma_f32_16x16x32_bf16(a, qf[1][ks], S[mt][1], 0, 0, 0);
;       }
;     bf16x8 pf[2][2];
; #pragma unroll
;     for (int n = 0; n < 2; ++n) {
;       float mx = S[0][n][0];
; #pragma unroll
;       for (int mt = 0; mt < 4; ++mt)
; #pragma unroll
;         for (int j = 0; j < 4; ++j) mx = fmaxf(mx, S[mt][n][j]);
;       mx = fmaxf(mx, shx(mx, 16, lane));
;       mx = fmaxf(mx, shx(mx, 32, lane));
;       float mnew = fmaxf(mrun[n], mx * sc);
;       float alpha = __builtin_amdgcn_exp2f(mrun[n] - mnew);
;       mrun[n] = mnew;
;       float ls = 0.f;
; #pragma unroll
;       for (int mt = 0; mt < 4; ++mt)
; #pragma unroll
;         for (int j = 0; j < 4; ++j) { float pv = __builtin_amdgcn_exp2f(S[mt][n][j] * sc - mnew); S[mt][n][j] = pv; ls += pv; }
;       lrun[n] = lrun[n] * alpha + ls;
; #pragma unroll
;       for (int i = 0; i < 8; ++i) O[i][n] *= alpha;
; #pragma unroll
;       for (int k2 = 0; k2 < 2; ++k2) {
;         u32x4 pk;
;         pk[0] = pack2(S[2 * k2][n][0], S[2 * k2][n][1]);
;         pk[1] = pack2(S[2 * k2][n][2], S[2 * k2][n][3]);
;         pk[2] = pack2(S[2 * k2 + 1][n][0], S[2 * k2 + 1][n][1]);
;         pk[3] = pack2(S[2 * k2 + 1][n][2], S[2 * k2 + 1][n][3]);
;         pf[n][k2] = __builtin_bit_cast(bf16x8, pk);
;       }
;     }
; #pragma unroll
;     for (int k2 = 0; k2 < 2; ++k2)
; #pragma unroll
;       for (int mv = 0; mv < 8; ++mv) {
;         const char* ap = vb + (mv * 16 + fr) * VSTR + (k2 * 32 + 4 * g) * 2;
;         uint2 h0 = *(const uint2*)(ap);
;         uint2 h1 = *(const uint2*)(ap + 32);
;         u32x4 avu = {h0.x, h0.y, h1.x, h1.y};
;         bf16x8 av = __builtin_bit_cast(bf16x8, avu);
;         O[mv][0] = __builtin_amdgcn_mfma_f32_16x16x32_bf16(av, pf[0][k2], O[mv][0], 0, 0, 0);
	v_mfma_f32_16x16x32_bf16 v[28:31], v[24:27], v[8:11], v[52:55]
	v_mfma_f32_16x16x32_bf16 v[24:27], v[24:27], v[12:15], v[48:51]
	s_nop 2
	ds_read_b128 v[48:51], v124 offset:40320
	s_waitcnt lgkmcnt(0)
	v_mfma_f32_16x16x32_bf16 v[52:55], v[48:51], v[8:11], v[60:63]
	v_mfma_f32_16x16x32_bf16 v[48:51], v[48:51], v[12:15], v[56:59]
	s_nop 2
	ds_read_b128 v[56:59], v124 offset:44672
	s_waitcnt lgkmcnt(0)
	v_mfma_f32_16x16x32_bf16 v[116:119], v[56:59], v[8:11], v[116:119]
	v_mfma_f32_16x16x32_bf16 v[112:115], v[56:59], v[12:15], v[112:115]
	ds_read_b128 v[56:59], v124 offset:49024
	s_waitcnt lgkmcnt(0)
	v_mfma_f32_16x16x32_bf16 v[8:11], v[56:59], v[8:11], v[16:19]
	s_nop 2
	ds_read_b128 v[16:19], v124 offset:36032
	v_mfma_f32_16x16x32_bf16 v[12:15], v[56:59], v[12:15], v[20:23]
	s_waitcnt lgkmcnt(0)
	v_mfma_f32_16x16x32_bf16 v[20:23], v[16:19], v[0:3], v[28:31]
	v_mfma_f32_16x16x32_bf16 v[56:59], v[16:19], v[4:7], v[24:27]
	ds_read_b128 v[16:19], v124 offset:40384
	s_waitcnt lgkmcnt(0)
	v_mfma_f32_16x16x32_bf16 v[24:27], v[16:19], v[0:3], v[52:55]
	v_mfma_f32_16x16x32_bf16 v[60:63], v[16:19], v[4:7], v[48:51]
	ds_read_b128 v[16:19], v124 offset:44736
	s_waitcnt lgkmcnt(0)
	v_mfma_f32_16x16x32_bf16 v[28:31], v[16:19], v[0:3], v[116:119]
	v_mfma_f32_16x16x32_bf16 v[112:115], v[16:19], v[4:7], v[112:115]
	ds_read_b128 v[16:19], v124 offset:49088
	s_waitcnt lgkmcnt(0)
	v_mfma_f32_16x16x32_bf16 v[116:119], v[16:19], v[4:7], v[12:15]
	v_max_f32_e32 v4, v21, v21
	v_max_f32_e32 v5, v20, v20
	v_max_f32_e32 v4, v5, v4
	v_max3_f32 v4, v4, v22, v23
	v_mfma_f32_16x16x32_bf16 v[0:3], v[16:19], v[0:3], v[8:11]
	v_max3_f32 v4, v4, v24, v25
	v_max3_f32 v4, v4, v26, v27
	v_max3_f32 v4, v4, v28, v29
	v_max3_f32 v4, v4, v30, v31
	s_nop 3
	v_max3_f32 v4, v4, v0, v1
	v_max3_f32 v4, v4, v2, v3
	ds_bpermute_b32 v5, v191, v4
	s_waitcnt lgkmcnt(0)
	v_max_f32_e32 v5, v5, v5
	v_max_f32_e32 v4, v4, v5
	ds_bpermute_b32 v5, v192, v4
	s_waitcnt lgkmcnt(0)
	v_max_f32_e32 v5, v5, v5
	v_max_f32_e32 v4, v4, v5
	v_mul_f32_e32 v4, 0x3e0293ee, v4
	v_max_f32_e32 v5, v203, v203
	v_max_f32_e32 v4, v5, v4
	v_sub_f32_e32 v5, v203, v4
	v_fma_f32 v6, v20, s0, -v4
	v_exp_f32_e32 v121, v6
	v_exp_f32_e32 v120, v5
	v_fma_f32 v6, v21, s0, -v4
	v_fma_f32 v0, v0, s0, -v4
	v_exp_f32_e32 v133, v0
	v_pk_mul_f32 v[20:21], v[80:81], v[120:121] op_sel_hi:[1,0]
	v_max_f32_e32 v80, v57, v57
	v_max_f32_e32 v81, v56, v56
	v_max_f32_e32 v80, v81, v80
	v_max3_f32 v80, v80, v58, v59
	v_max3_f32 v80, v80, v60, v61
	v_max3_f32 v80, v80, v62, v63
	v_max3_f32 v80, v80, v112, v113
	v_max3_f32 v80, v80, v114, v115
	v_max3_f32 v80, v80, v116, v117
	v_max3_f32 v80, v80, v118, v119
	ds_bpermute_b32 v81, v191, v80
	v_fma_f32 v0, v1, s0, -v4
	v_pk_mul_f32 v[52:53], v[92:93], v[120:121] op_sel_hi:[1,0]
	v_exp_f32_e32 v134, v0
	v_fma_f32 v0, v2, s0, -v4
	s_waitcnt lgkmcnt(0)
	v_max_f32_e32 v81, v81, v81
	v_max_f32_e32 v80, v80, v81
	ds_bpermute_b32 v81, v192, v80
	v_pk_mul_f32 v[54:55], v[94:95], v[120:121] op_sel_hi:[1,0]
	v_exp_f32_e32 v135, v0
	v_fma_f32 v0, v3, s0, -v4
	v_exp_f32_e32 v136, v0
	s_waitcnt lgkmcnt(0)
	v_max_f32_e32 v81, v81, v81
	v_max_f32_e32 v80, v80, v81
	v_mul_f32_e32 v80, 0x3e0293ee, v80
	v_max_f32_e32 v81, v204, v204
	v_max_f32_e32 v80, v81, v80
	v_fma_f32 v56, v56, s0, -v80
	v_exp_f32_e32 v93, v56
	v_fma_f32 v56, v57, s0, -v80
	v_exp_f32_e32 v94, v56
	v_fma_f32 v56, v58, s0, -v80
	v_exp_f32_e32 v95, v56
	v_fma_f32 v56, v59, s0, -v80
	v_pk_mul_f32 v[0:1], v[96:97], v[120:121] op_sel_hi:[1,0]
	v_exp_f32_e32 v96, v56
	v_fma_f32 v56, v60, s0, -v80
	v_exp_f32_e32 v97, v56
	v_fma_f32 v56, v61, s0, -v80
	v_pk_mul_f32 v[2:3], v[98:99], v[120:121] op_sel_hi:[1,0]
	v_exp_f32_e32 v98, v56
	v_fma_f32 v56, v62, s0, -v80
	v_exp_f32_e32 v99, v56
	v_fma_f32 v56, v63, s0, -v80
	v_pk_mul_f32 v[8:9], v[100:101], v[120:121] op_sel_hi:[1,0]
	v_sub_f32_e32 v81, v204, v80
	v_exp_f32_e32 v100, v56
	v_fma_f32 v56, v112, s0, -v80
	v_exp_f32_e32 v101, v56
	v_fma_f32 v56, v113, s0, -v80
	v_exp_f32_e32 v92, v81
	v_pk_mul_f32 v[10:11], v[102:103], v[120:121] op_sel_hi:[1,0]
	v_exp_f32_e32 v102, v56
	v_fma_f32 v56, v114, s0, -v80
	v_exp_f32_e32 v122, v6
	v_fma_f32 v6, v22, s0, -v4
	v_pk_mul_f32 v[16:17], v[108:109], v[120:121] op_sel_hi:[1,0]
	v_exp_f32_e32 v103, v56
	v_fma_f32 v56, v115, s0, -v80
	v_add_u32_e32 v109, v193, v194
	v_exp_f32_e32 v123, v6
	v_fma_f32 v6, v23, s0, -v4
	v_pk_mul_f32 v[12:13], v[104:105], v[120:121] op_sel_hi:[1,0]
	v_exp_f32_e32 v104, v56
	v_fma_f32 v56, v116, s0, -v80
	v_add_u32_e32 v143, 0xf000, v109
	v_exp_f32_e32 v124, v6
	v_fma_f32 v6, v24, s0, -v4
	v_exp_f32_e32 v105, v56
	v_fma_f32 v56, v117, s0, -v80
	v_pk_mul_f32 v[116:117], v[38:39], v[92:93] op_sel_hi:[1,0]
	v_pk_mul_f32 v[114:115], v[36:37], v[92:93] op_sel_hi:[1,0]
	v_pk_mul_f32 v[38:39], v[78:79], v[92:93] op_sel_hi:[1,0]
	v_pk_mul_f32 v[36:37], v[76:77], v[92:93] op_sel_hi:[1,0]
	ds_read2_b64 v[76:79], v143 offset0:128 offset1:132
	v_exp_f32_e32 v125, v6
	v_fma_f32 v6, v25, s0, -v4
	v_exp_f32_e32 v126, v6
	v_fma_f32 v6, v26, s0, -v4
	v_exp_f32_e32 v127, v6
	v_fma_f32 v6, v27, s0, -v4
	v_exp_f32_e32 v128, v6
	v_fma_f32 v6, v28, s0, -v4
	v_exp_f32_e32 v129, v6
	v_fma_f32 v6, v29, s0, -v4
	v_exp_f32_e32 v130, v6
	v_fma_f32 v6, v30, s0, -v4
	v_exp_f32_e32 v131, v6
	v_fma_f32 v6, v31, s0, -v4
	v_pk_mul_f32 v[14:15], v[106:107], v[120:121] op_sel_hi:[1,0]
	v_exp_f32_e32 v106, v56
	v_fma_f32 v56, v118, s0, -v80
	v_exp_f32_e32 v132, v6
	v_pk_mul_f32 v[50:51], v[90:91], v[120:121] op_sel_hi:[1,0]
	v_pk_mul_f32 v[48:49], v[88:89], v[120:121] op_sel_hi:[1,0]
	v_pk_mul_f32 v[22:23], v[82:83], v[120:121] op_sel_hi:[1,0]
	v_pk_mul_f32 v[18:19], v[110:111], v[120:121] op_sel_hi:[1,0]
	v_cvt_pk_bf16_f32 v4, v121, v122
	v_cvt_pk_bf16_f32 v5, v123, v124
	v_cvt_pk_bf16_f32 v6, v125, v126
	v_cvt_pk_bf16_f32 v7, v127, v128
	v_exp_f32_e32 v107, v56
	v_fma_f32 v56, v119, s0, -v80
	v_pk_mul_f32 v[90:91], v[42:43], v[92:93] op_sel_hi:[1,0]
	v_pk_mul_f32 v[88:89], v[40:41], v[92:93] op_sel_hi:[1,0]
	v_pk_mul_f32 v[82:83], v[66:67], v[92:93] op_sel_hi:[1,0]
	v_pk_mul_f32 v[80:81], v[64:65], v[92:93] op_sel_hi:[1,0]
	v_cvt_pk_bf16_f32 v40, v93, v94
	v_cvt_pk_bf16_f32 v41, v95, v96
	v_cvt_pk_bf16_f32 v42, v97, v98
	v_cvt_pk_bf16_f32 v43, v99, v100
	v_add_u32_e32 v142, 0xe800, v109
	v_add_u32_e32 v146, 0xf800, v109
	v_pk_mul_f32 v[26:27], v[86:87], v[120:121] op_sel_hi:[1,0]
	v_pk_mul_f32 v[24:25], v[84:85], v[120:121] op_sel_hi:[1,0]
	v_pk_mul_f32 v[86:87], v[46:47], v[92:93] op_sel_hi:[1,0]
	v_pk_mul_f32 v[84:85], v[44:45], v[92:93] op_sel_hi:[1,0]
	v_pk_mul_f32 v[46:47], v[74:75], v[92:93] op_sel_hi:[1,0]
	v_pk_mul_f32 v[44:45], v[72:73], v[92:93] op_sel_hi:[1,0]
	ds_read2_b64 v[72:75], v142 offset0:96 offset1:100
	s_waitcnt lgkmcnt(1)
; #define AT_LWRITE(R, V, bi) do { char* _base = smem + (bi) * STB; \
;     *(uint4*)(_base + krow0 * KSTR + kcc0 * 16) = R##0; \
;     *(uint4*)(_base + krow1 * KSTR + kcc1 * 16) = R##1; \
;     if (NKC > 2) *(uint4*)(_base + krow2 * KSTR + kcc2 * 16) = R##2; \
;     *(uint4*)(_base + KTB + vrow0 * VSTR + vcc * 16) = V##0; \
;     *(uint4*)(_base + KTB + vrow1 * VSTR + vcc * 16) = V##1; } while (0)
; template <int DK>
; __device__ __forceinline__ void attn_item(const u16* __restrict__ Qp, const u16* __restrict__ Kp, const u16* __restrict__ Vt,
;                                           u16* __restrict__ Yo, float sc, char* smem) {
;     ...
; #pragma unroll
;     for (int k2 = 0; k2 < 2; ++k2)
; #pragma unroll
;       for (int mv = 0; mv < 8; ++mv) {
;         const char* ap = vb + (mv * 16 + fr) * VSTR + (k2 * 32 + 4 * g) * 2;
;         uint2 h0 = *(const uint2*)(ap);
;         uint2 h1 = *(const uint2*)(ap + 32);
;         u32x4 avu = {h0.x, h0.y, h1.x, h1.y};
;         bf16x8 av = __builtin_bit_cast(bf16x8, avu);
;         O[mv][0] = __builtin_amdgcn_mfma_f32_16x16x32_bf16(av, pf[0][k2], O[mv][0], 0, 0, 0);
;         O[mv][1] = __builtin_amdgcn_mfma_f32_16x16x32_bf16(av, pf[1][k2], O[mv][1], 0, 0, 0);
;       }
;     if (kt + 1 < 32) { if (PF2 && (kt & 1)) AT_LWRITE(ks, vs, (kt + 1) & 1); else AT_LWRITE(kr, vr, (kt + 1) & 1); }
;     __syncthreads();
	v_mfma_f32_16x16x32_bf16 v[16:19], v[76:79], v[4:7], v[16:19]
	v_add_u32_e32 v118, 0xd000, v109
	v_add_u32_e32 v137, 0xe000, v109
	v_pk_mul_f32 v[62:63], v[70:71], v[92:93] op_sel_hi:[1,0]
	v_mfma_f32_16x16x32_bf16 v[76:79], v[76:79], v[40:43], v[80:83]
	v_mul_f32_e64 v60, v68, v92
	v_mul_f32_e64 v61, v69, v92
	ds_read2_b64 v[68:71], v137 offset0:64 offset1:68
	ds_read2_b64 v[64:67], v118 offset1:4
	ds_read2_b64 v[80:83], v146 offset0:160 offset1:164
	s_waitcnt lgkmcnt(3)
	v_mfma_f32_16x16x32_bf16 v[20:23], v[72:75], v[4:7], v[20:23]
	v_mul_f32_e64 v112, v34, v92
	v_mul_f32_e64 v113, v35, v92
	v_pk_mul_f32 v[110:111], v[32:33], v[92:93] op_sel_hi:[1,0]
	v_add_u32_e32 v119, 0xd800, v109
	v_mfma_f32_16x16x32_bf16 v[72:75], v[72:75], v[40:43], v[84:87]
	v_exp_f32_e32 v108, v56
	v_cvt_pk_bf16_f32 v28, v129, v130
	v_cvt_pk_bf16_f32 v29, v131, v132
	s_waitcnt lgkmcnt(0)
	v_mfma_f32_16x16x32_bf16 v[84:87], v[80:83], v[4:7], v[12:15]
	v_cvt_pk_bf16_f32 v30, v133, v134
	v_cvt_pk_bf16_f32 v31, v135, v136
	v_cvt_pk_bf16_f32 v32, v101, v102
	v_add_u32_e32 v12, 0x3000, v118
	ds_read2_b64 v[12:15], v12 offset0:192 offset1:196
	v_mfma_f32_16x16x32_bf16 v[24:27], v[68:71], v[4:7], v[24:27]
	v_cvt_pk_bf16_f32 v33, v103, v104
	v_cvt_pk_bf16_f32 v34, v105, v106
	v_cvt_pk_bf16_f32 v35, v107, v108
	v_mfma_f32_16x16x32_bf16 v[68:71], v[68:71], v[40:43], v[88:91]
	v_add_u32_e32 v109, 0xd040, v109
	s_waitcnt lgkmcnt(0)
	v_mfma_f32_16x16x32_bf16 v[88:91], v[12:15], v[4:7], v[8:11]
	s_nop 2
	v_add_u32_e32 v8, 0x3800, v118
	v_mfma_f32_16x16x32_bf16 v[56:59], v[64:67], v[4:7], v[52:55]
	ds_read2_b64 v[8:11], v8 offset0:224 offset1:228
	v_mfma_f32_16x16x32_bf16 v[52:55], v[64:67], v[40:43], v[110:113]
	ds_read2_b64 v[64:67], v119 offset0:32 offset1:36
	s_waitcnt lgkmcnt(0)
	v_mfma_f32_16x16x32_bf16 v[48:51], v[64:67], v[4:7], v[48:51]
	v_mfma_f32_16x16x32_bf16 v[64:67], v[64:67], v[40:43], v[114:117]
	v_mfma_f32_16x16x32_bf16 v[110:113], v[12:15], v[40:43], v[44:47]
	ds_read2_b64 v[12:15], v142 offset0:104 offset1:108
	v_mfma_f32_16x16x32_bf16 v[114:117], v[8:11], v[4:7], v[0:3]
	ds_read2_b64 v[4:7], v119 offset0:40 offset1:44
	v_mfma_f32_16x16x32_bf16 v[138:141], v[8:11], v[40:43], v[36:39]
	s_nop 0
	ds_read2_b64 v[0:3], v118 offset0:8 offset1:12
	ds_read2_b64 v[8:11], v137 offset0:72 offset1:76
	v_mfma_f32_16x16x32_bf16 v[80:83], v[80:83], v[40:43], v[60:63]
	s_waitcnt lgkmcnt(2)
	v_mfma_f32_16x16x32_bf16 v[60:63], v[4:7], v[28:31], v[48:51]
	v_mfma_f32_16x16x32_bf16 v[48:51], v[12:15], v[28:31], v[20:23]
	s_nop 2
	ds_read2_b64 v[20:23], v143 offset0:136 offset1:140
	s_waitcnt lgkmcnt(2)
	v_mfma_f32_16x16x32_bf16 v[56:59], v[0:3], v[28:31], v[56:59]
	v_mfma_f32_16x16x32_bf16 v[0:3], v[0:3], v[32:35], v[52:55]
	v_mfma_f32_16x16x32_bf16 v[4:7], v[4:7], v[32:35], v[64:67]
	s_waitcnt lgkmcnt(1)
	v_mfma_f32_16x16x32_bf16 v[52:55], v[8:11], v[28:31], v[24:27]
	s_nop 0
	v_add_u32_e32 v64, 0x3800, v109
	s_nop 0
	v_add_u32_e32 v24, 0x3000, v109
	v_mfma_f32_16x16x32_bf16 v[8:11], v[8:11], v[32:35], v[68:71]
	ds_read2_b64 v[24:27], v24 offset0:192 offset1:196
	s_waitcnt lgkmcnt(1)
	v_mfma_f32_16x16x32_bf16 v[40:43], v[20:23], v[28:31], v[16:19]
	ds_read2_b64 v[68:71], v64 offset0:224 offset1:228
	v_mfma_f32_16x16x32_bf16 v[16:19], v[20:23], v[32:35], v[76:79]
	ds_read2_b64 v[20:23], v146 offset0:168 offset1:172
	s_waitcnt lgkmcnt(0)
	s_barrier
; template <int DK>
; __device__ __forceinline__ void attn_item(const u16* __restrict__ Qp, const u16* __restrict__ Kp, const u16* __restrict__ Vt,
;                                           u16* __restrict__ Yo, float sc, char* smem) {
;     ...
;       float ls = 0.f;
; #pragma unroll
;       for (int mt = 0; mt < 4; ++mt)
; #pragma unroll
;         for (int j = 0; j < 4; ++j) { float pv = __builtin_amdgcn_exp2f(S[mt][n][j] * sc - mnew); S[mt][n][j] = pv; ls += pv; }
;       lrun[n] = lrun[n] * alpha + ls;
;     ...
; #pragma unroll
;   for (int n = 0; n < 2; ++n) {
;     float l = lrun[n];
;     l += shx(l, 16, lane); l += shx(l, 32, lane);
;     float inv = 1.f / l;
;     int wv2 = wave, fr2 = fr, g2 = g;
;     asm volatile("" : "+v"(wv2), "+v"(fr2), "+v"(g2));
;     int q = wv2 * 32 + n * 16 + fr2;
; #pragma unroll
;     for (int mv = 0; mv < 8; ++mv) {
;       uint2 w;
;       w.x = pack2(O[mv][n][0] * inv, O[mv][n][1] * inv);
;       w.y = pack2(O[mv][n][2] * inv, O[mv][n][3] * inv);
;       *(uint2*)(Yo + (unsigned)(q * 512 + mv * 16 + 4 * g2)) = w;
;     }
	v_mfma_f32_16x16x32_bf16 v[12:15], v[12:15], v[32:35], v[72:75]
	v_mfma_f32_16x16x32_bf16 v[44:47], v[20:23], v[28:31], v[84:87]
	v_mfma_f32_16x16x32_bf16 v[20:23], v[20:23], v[32:35], v[80:83]
	v_mfma_f32_16x16x32_bf16 v[36:39], v[24:27], v[28:31], v[88:91]
	v_mfma_f32_16x16x32_bf16 v[24:27], v[24:27], v[32:35], v[110:113]
	v_mfma_f32_16x16x32_bf16 v[64:67], v[68:71], v[28:31], v[114:117]
	v_mfma_f32_16x16x32_bf16 v[28:31], v[68:71], v[32:35], v[138:141]
	v_add_f32_e32 v32, 0, v93
	v_add_f32_e32 v32, v94, v32
	v_add_f32_e32 v32, v95, v32
	v_add_f32_e32 v32, v96, v32
	v_add_f32_e32 v32, v97, v32
	v_add_f32_e32 v32, v98, v32
	v_add_f32_e32 v32, v99, v32
	v_add_f32_e32 v32, v100, v32
	v_add_f32_e32 v32, v101, v32
	v_add_f32_e32 v32, v102, v32
	v_add_f32_e32 v32, v103, v32
	v_add_f32_e32 v32, v104, v32
	v_add_f32_e32 v32, v105, v32
	v_add_f32_e32 v32, v106, v32
	v_add_f32_e32 v32, v107, v32
	v_add_f32_e32 v68, v108, v32
	v_add_f32_e32 v32, 0, v121
	v_add_f32_e32 v32, v122, v32
	v_add_f32_e32 v32, v123, v32
	v_add_f32_e32 v32, v124, v32
	v_add_f32_e32 v32, v125, v32
	v_add_f32_e32 v32, v126, v32
	v_add_f32_e32 v32, v127, v32
	v_add_f32_e32 v32, v128, v32
	v_add_f32_e32 v32, v129, v32
	v_add_f32_e32 v32, v130, v32
	v_add_f32_e32 v32, v131, v32
	v_add_f32_e32 v32, v132, v32
	v_add_f32_e32 v32, v133, v32
	v_add_f32_e32 v32, v134, v32
	v_add_f32_e32 v32, v135, v32
	v_add_f32_e32 v32, v136, v32
	v_fmac_f32_e32 v32, v145, v120
	ds_bpermute_b32 v33, v191, v32
	v_fmac_f32_e32 v68, v144, v92
	s_waitcnt lgkmcnt(0)
	v_add_f32_e32 v32, v32, v33
	ds_bpermute_b32 v33, v192, v32
	s_waitcnt lgkmcnt(0)
	v_add_f32_e32 v32, v32, v33
	v_div_scale_f32 v33, s[2:3], v32, v32, 1.0
	v_rcp_f32_e32 v34, v33
	s_nop 0
	v_fma_f32 v35, -v33, v34, 1.0
	v_fmac_f32_e32 v34, v35, v34
	v_div_scale_f32 v35, vcc, 1.0, v32, 1.0
	v_mul_f32_e32 v69, v35, v34
	v_fma_f32 v70, -v33, v69, v35
	v_fmac_f32_e32 v69, v70, v34
	v_fma_f32 v33, -v33, v69, v35
	v_div_fmas_f32 v33, v33, v34, v69
	v_div_fixup_f32 v32, v33, v32, 1.0
	v_mov_b32_e32 v33, v237
	v_mov_b32_e32 v34, v239
	v_mov_b32_e32 v35, v238
	s_nop 0
	v_lshlrev_b32_e32 v33, 14, v33
	v_lshlrev_b32_e32 v35, 9, v35
	v_lshlrev_b32_e32 v34, 2, v34
	v_add3_u32 v178, v33, v35, v34
	v_pk_mul_f32 v[34:35], v[56:57], v[32:33] op_sel_hi:[1,0]
	v_pk_mul_f32 v[56:57], v[58:59], v[32:33] op_sel_hi:[1,0]
	v_cvt_pk_bf16_f32 v34, v34, v35
	v_cvt_pk_bf16_f32 v35, v56, v57
	v_lshl_add_u64 v[56:57], v[178:179], 1, s[8:9]
	global_store_dwordx2 v[56:57], v[34:35], off
	v_pk_mul_f32 v[34:35], v[60:61], v[32:33] op_sel_hi:[1,0]
	v_pk_mul_f32 v[56:57], v[62:63], v[32:33] op_sel_hi:[1,0]
	v_cvt_pk_bf16_f32 v34, v34, v35
	v_cvt_pk_bf16_f32 v35, v56, v57
	v_add_u32_e32 v56, 16, v178
	v_mov_b32_e32 v57, v179
	v_lshl_add_u64 v[56:57], v[56:57], 1, s[8:9]
	global_store_dwordx2 v[56:57], v[34:35], off
	v_pk_mul_f32 v[34:35], v[52:53], v[32:33] op_sel_hi:[1,0]
	v_pk_mul_f32 v[52:53], v[54:55], v[32:33] op_sel_hi:[1,0]
	v_cvt_pk_bf16_f32 v34, v34, v35
	v_cvt_pk_bf16_f32 v35, v52, v53
	v_add_u32_e32 v52, 32, v178
	v_mov_b32_e32 v53, v179
	v_lshl_add_u64 v[52:53], v[52:53], 1, s[8:9]
	global_store_dwordx2 v[52:53], v[34:35], off
	v_pk_mul_f32 v[34:35], v[48:49], v[32:33] op_sel_hi:[1,0]
	v_pk_mul_f32 v[48:49], v[50:51], v[32:33] op_sel_hi:[1,0]
	v_cvt_pk_bf16_f32 v34, v34, v35
	v_cvt_pk_bf16_f32 v35, v48, v49
	v_add_u32_e32 v48, 48, v178
	v_mov_b32_e32 v49, v179
	v_lshl_add_u64 v[48:49], v[48:49], 1, s[8:9]
	global_store_dwordx2 v[48:49], v[34:35], off
	v_pk_mul_f32 v[34:35], v[40:41], v[32:33] op_sel_hi:[1,0]
	v_pk_mul_f32 v[40:41], v[42:43], v[32:33] op_sel_hi:[1,0]
	v_cvt_pk_bf16_f32 v34, v34, v35
	v_cvt_pk_bf16_f32 v35, v40, v41
	v_add_u32_e32 v40, 64, v178
	v_mov_b32_e32 v41, v179
	v_lshl_add_u64 v[40:41], v[40:41], 1, s[8:9]
	global_store_dwordx2 v[40:41], v[34:35], off
	v_pk_mul_f32 v[34:35], v[44:45], v[32:33] op_sel_hi:[1,0]
	v_pk_mul_f32 v[40:41], v[46:47], v[32:33] op_sel_hi:[1,0]
	v_cvt_pk_bf16_f32 v34, v34, v35
	v_cvt_pk_bf16_f32 v35, v40, v41
	v_add_u32_e32 v40, 0x50, v178
	v_mov_b32_e32 v41, v179
	v_lshl_add_u64 v[40:41], v[40:41], 1, s[8:9]
	global_store_dwordx2 v[40:41], v[34:35], off
	v_pk_mul_f32 v[34:35], v[36:37], v[32:33] op_sel_hi:[1,0]
	v_pk_mul_f32 v[36:37], v[38:39], v[32:33] op_sel_hi:[1,0]
	v_cvt_pk_bf16_f32 v34, v34, v35
	v_cvt_pk_bf16_f32 v35, v36, v37
	v_add_u32_e32 v36, 0x60, v178
	v_mov_b32_e32 v37, v179
	v_lshl_add_u64 v[36:37], v[36:37], 1, s[8:9]
	global_store_dwordx2 v[36:37], v[34:35], off
	v_pk_mul_f32 v[34:35], v[64:65], v[32:33] op_sel_hi:[1,0]
	v_pk_mul_f32 v[32:33], v[66:67], v[32:33] op_sel_hi:[1,0]
	v_add_u32_e32 v178, 0x70, v178
	v_cvt_pk_bf16_f32 v34, v34, v35
	v_cvt_pk_bf16_f32 v35, v32, v33
	v_lshl_add_u64 v[32:33], v[178:179], 1, s[8:9]
	global_store_dwordx2 v[32:33], v[34:35], off
	ds_bpermute_b32 v32, v191, v68
	s_waitcnt lgkmcnt(0)
	v_add_f32_e32 v32, v68, v32
	ds_bpermute_b32 v33, v192, v32
	s_waitcnt lgkmcnt(0)
	v_add_f32_e32 v32, v32, v33
	s_and_b64 vcc, exec, s[6:7]
	s_cbranch_vccz .LBB0_2442
	s_branch .LBB0_2469
